# in-proj tail-round loop: staging DMA issued between the MFMAs of the (short) matrix blocks instead of in the load segments; leading half waits at block end, trailing half issues one slot earlier
# speedup vs baseline: 1.0047x; 1.0006x over previous
; #define PG8_STAGE(bufoff, gbase, voff) do { _Pragma("unroll") for (int _i = 0; _i < 2; ++_i) \
;         __builtin_amdgcn_global_load_lds((const unsigned*)((const char*)(gbase) + (voff)[_i]), (PG8_LAS unsigned*)(lds + (bufoff) + ldsw + _i * 8192), 16, 0, 0); } while (0)
; #define PG8_LDA(dst, b, h) do { _Pragma("unroll") for (int m = 0; m < 4; ++m) _Pragma("unroll") for (int k = 0; k < 2; ++k) dst[m][k] = *(const PG8_LAS bf16x8*)(lds + PG8_SA(b, h) + aoff + m * 2048 + k * 1024); } while (0)
; #define PG8_LDB(dst, b, h) do { _Pragma("unroll") for (int n = 0; n < 2; ++n) _Pragma("unroll") for (int k = 0; k < 2; ++k) dst[n][k] = *(const PG8_LAS bf16x8*)(lds + PG8_SB(b, h) + boff + n * 2048 + k * 1024); } while (0)
; #define PG8_MMA(ai, bj, At, Bt) do { __builtin_amdgcn_s_setprio(1); _Pragma("unroll") for (int m = 0; m < 4; ++m) _Pragma("unroll") for (int n = 0; n < 2; ++n) _Pragma("unroll") for (int k = 0; k < 2; ++k) \
;         acc[ai][bj][m][n] = __builtin_amdgcn_mfma_f32_16x16x32_bf16(Bt[n][k], At[m][k], acc[ai][bj][m][n], 0, 0, 0); __builtin_amdgcn_s_setprio(0); } while (0)
; #define PG8_WAIT_V(n) asm volatile("s_waitcnt vmcnt(" #n ")" ::: "memory")
; #define PG8_WAIT_L(n) asm volatile("s_waitcnt lgkmcnt(" #n ")" ::: "memory")
; #define PG8_BAR __builtin_amdgcn_s_barrier()
; #define PG8_SCHED __builtin_amdgcn_sched_barrier(0)
; template <class Epi, class Sched, bool ALIGN_EPI = false, bool SP2 = false>
; __device__ __forceinline__ void gemm_phase(PG8_LAS unsigned char* lds, const Gemm g, const Sched& S, const Epi& E) {
;     ...
;             PG8_LDB(B0, 0, 0); PG8_LDB(B1, 0, 1); PG8_SCHED; PG8_LDA(At, 0, 0); PG8_STAGE(PG8_SA(1, 1), a1 + hstep, voffA);
;             PG8_WAIT_V(8); PG8_WAIT_L(0); PG8_BAR; PG8_MMA(0, 0, At, B0); PG8_MMA(0, 1, At, B1); PG8_BAR; PG8_SCHED;
;             PG8_LDA(At, 0, 1); PG8_STAGE(PG8_SB(0, 0), b2, voffB); PG8_STAGE(PG8_SB(0, 1), b2 + hstep, voffB); PG8_STAGE(PG8_SA(0, 0), a2, voffA);
;             PG8_WAIT_V(8); PG8_WAIT_L(0); PG8_BAR; PG8_MMA(1, 0, At, B0); PG8_MMA(1, 1, At, B1); PG8_BAR; PG8_SCHED;
.Ltail_loop:
	ds_read_b128 v[114:117], v242
	ds_read_b128 v[118:121], v242 offset:1024
	ds_read_b128 v[130:133], v242 offset:2048
	ds_read_b128 v[134:137], v242 offset:3072
	ds_read_b128 v[180:183], v178
	ds_read_b128 v[184:187], v178 offset:1024
	ds_read_b128 v[188:191], v178 offset:2048
	ds_read_b128 v[192:195], v178 offset:3072
	ds_read_b128 v[196:199], v178 offset:4096
	ds_read_b128 v[200:203], v178 offset:5120
	ds_read_b128 v[208:211], v178 offset:6144
	ds_read_b128 v[230:233], v178 offset:7168
	s_add_u32 s40, s34, 0xfff80080
	s_addc_u32 s41, s35, -1
	s_cmp_eq_u32 s46, 28
	s_cselect_b32 s43, s15, s41
	s_cselect_b32 s42, s19, s40
	s_cselect_b32 s41, s17, s45
	s_cselect_b32 s40, s37, s44
	s_mov_b64 vcc, s[2:3]
	s_cbranch_vccnz .Ltm_s0
	s_add_i32 m0, s8, 0xc000
	s_nop 0
	global_load_lds_dwordx4 v164, s[34:35]
	s_add_i32 m0, s8, 0xe000
	s_nop 0
	global_load_lds_dwordx4 v166, s[34:35]
	s_waitcnt vmcnt(6)
.Ltm_s0:
	s_waitcnt lgkmcnt(0)
	s_barrier
	s_mov_b64 vcc, s[2:3]
	s_cbranch_vccz .Ltm_t0
	s_setprio 1
	v_mfma_f32_16x16x32_bf16 v[142:145], v[114:117], v[180:183], v[142:145]
	s_add_i32 m0, s8, 0xc000
	v_mfma_f32_16x16x32_bf16 v[138:141], v[130:133], v[180:183], v[138:141]
	global_load_lds_dwordx4 v164, s[34:35]
	v_mfma_f32_16x16x32_bf16 v[110:113], v[114:117], v[188:191], v[110:113]
	s_add_i32 m0, s8, 0xe000
	v_mfma_f32_16x16x32_bf16 v[106:109], v[130:133], v[188:191], v[106:109]
	global_load_lds_dwordx4 v166, s[34:35]
	v_mfma_f32_16x16x32_bf16 v[94:97], v[114:117], v[196:199], v[94:97]
	v_mfma_f32_16x16x32_bf16 v[90:93], v[130:133], v[196:199], v[90:93]
	v_mfma_f32_16x16x32_bf16 v[78:81], v[114:117], v[208:211], v[78:81]
	v_mfma_f32_16x16x32_bf16 v[74:77], v[130:133], v[208:211], v[74:77]
	v_mfma_f32_16x16x32_bf16 v[142:145], v[118:121], v[184:187], v[142:145]
	v_mfma_f32_16x16x32_bf16 v[138:141], v[134:137], v[184:187], v[138:141]
	v_mfma_f32_16x16x32_bf16 v[110:113], v[118:121], v[192:195], v[110:113]
	v_mfma_f32_16x16x32_bf16 v[106:109], v[134:137], v[192:195], v[106:109]
	v_mfma_f32_16x16x32_bf16 v[94:97], v[118:121], v[200:203], v[94:97]
	v_mfma_f32_16x16x32_bf16 v[90:93], v[134:137], v[200:203], v[90:93]
	v_mfma_f32_16x16x32_bf16 v[78:81], v[118:121], v[230:233], v[78:81]
	v_mfma_f32_16x16x32_bf16 v[74:77], v[134:137], v[230:233], v[74:77]
	s_setprio 0
	s_waitcnt vmcnt(6)
	s_branch .Ltm_e0
.Ltm_t0:
	s_setprio 1
	v_mfma_f32_16x16x32_bf16 v[142:145], v[114:117], v[180:183], v[142:145]
	s_add_i32 s47, s88, s6
	v_mfma_f32_16x16x32_bf16 v[138:141], v[130:133], v[180:183], v[138:141]
	s_mov_b32 m0, s47
	v_mfma_f32_16x16x32_bf16 v[110:113], v[114:117], v[188:191], v[110:113]
	global_load_lds_dwordx4 v0, s[40:41]
	v_mfma_f32_16x16x32_bf16 v[106:109], v[130:133], v[188:191], v[106:109]
	s_add_i32 m0, s47, 0x2000
	v_mfma_f32_16x16x32_bf16 v[94:97], v[114:117], v[196:199], v[94:97]
	global_load_lds_dwordx4 v154, s[40:41]
	v_mfma_f32_16x16x32_bf16 v[90:93], v[130:133], v[196:199], v[90:93]
	s_mov_b32 m0, s8
	v_mfma_f32_16x16x32_bf16 v[78:81], v[114:117], v[208:211], v[78:81]
	global_load_lds_dwordx4 v158, s[42:43]
	v_mfma_f32_16x16x32_bf16 v[74:77], v[130:133], v[208:211], v[74:77]
	s_mov_b32 m0, s9
	v_mfma_f32_16x16x32_bf16 v[142:145], v[118:121], v[184:187], v[142:145]
	global_load_lds_dwordx4 v156, s[42:43]
	v_mfma_f32_16x16x32_bf16 v[138:141], v[134:137], v[184:187], v[138:141]
	v_mfma_f32_16x16x32_bf16 v[110:113], v[118:121], v[192:195], v[110:113]
	v_mfma_f32_16x16x32_bf16 v[106:109], v[134:137], v[192:195], v[106:109]
	v_mfma_f32_16x16x32_bf16 v[94:97], v[118:121], v[200:203], v[94:97]
	v_mfma_f32_16x16x32_bf16 v[90:93], v[134:137], v[200:203], v[90:93]
	v_mfma_f32_16x16x32_bf16 v[78:81], v[118:121], v[230:233], v[78:81]
	v_mfma_f32_16x16x32_bf16 v[74:77], v[134:137], v[230:233], v[74:77]
	s_setprio 0
.Ltm_e0:
	s_barrier
	ds_read_b128 v[180:183], v178 offset:16384
	ds_read_b128 v[184:187], v178 offset:17408
	ds_read_b128 v[188:191], v178 offset:18432
	ds_read_b128 v[192:195], v178 offset:19456
	ds_read_b128 v[196:199], v178 offset:20480
	ds_read_b128 v[200:203], v178 offset:21504
	ds_read_b128 v[208:211], v178 offset:22528
	ds_read_b128 v[230:233], v178 offset:23552
	s_mov_b64 vcc, s[2:3]
	s_cbranch_vccnz .Ltm_s1
	s_waitcnt vmcnt(6)
.Ltm_s1:
	s_waitcnt lgkmcnt(0)
	s_barrier
	s_mov_b64 vcc, s[2:3]
	s_cbranch_vccz .Ltm_t1
	s_setprio 1
	v_mfma_f32_16x16x32_bf16 v[62:65], v[114:117], v[180:183], v[62:65]
	s_add_i32 s47, s88, s6
	v_mfma_f32_16x16x32_bf16 v[58:61], v[130:133], v[180:183], v[58:61]
	s_mov_b32 m0, s47
	v_mfma_f32_16x16x32_bf16 v[46:49], v[114:117], v[188:191], v[46:49]
	global_load_lds_dwordx4 v0, s[40:41]
	v_mfma_f32_16x16x32_bf16 v[42:45], v[130:133], v[188:191], v[42:45]
	s_add_i32 m0, s47, 0x2000
	v_mfma_f32_16x16x32_bf16 v[30:33], v[114:117], v[196:199], v[30:33]
	global_load_lds_dwordx4 v154, s[40:41]
	v_mfma_f32_16x16x32_bf16 v[26:29], v[130:133], v[196:199], v[26:29]
	s_mov_b32 m0, s8
	v_mfma_f32_16x16x32_bf16 v[14:17], v[114:117], v[208:211], v[14:17]
	global_load_lds_dwordx4 v158, s[42:43]
	v_mfma_f32_16x16x32_bf16 v[10:13], v[130:133], v[208:211], v[10:13]
	s_mov_b32 m0, s9
	v_mfma_f32_16x16x32_bf16 v[62:65], v[118:121], v[184:187], v[62:65]
	global_load_lds_dwordx4 v156, s[42:43]
	v_mfma_f32_16x16x32_bf16 v[58:61], v[134:137], v[184:187], v[58:61]
	v_mfma_f32_16x16x32_bf16 v[46:49], v[118:121], v[192:195], v[46:49]
	v_mfma_f32_16x16x32_bf16 v[42:45], v[134:137], v[192:195], v[42:45]
	v_mfma_f32_16x16x32_bf16 v[30:33], v[118:121], v[200:203], v[30:33]
	v_mfma_f32_16x16x32_bf16 v[26:29], v[134:137], v[200:203], v[26:29]
	v_mfma_f32_16x16x32_bf16 v[14:17], v[118:121], v[230:233], v[14:17]
	v_mfma_f32_16x16x32_bf16 v[10:13], v[134:137], v[230:233], v[10:13]
	s_setprio 0
	s_waitcnt vmcnt(6)
	s_branch .Ltm_e1
; #define PG8_STAGE(bufoff, gbase, voff) do { _Pragma("unroll") for (int _i = 0; _i < 2; ++_i) \
;         __builtin_amdgcn_global_load_lds((const unsigned*)((const char*)(gbase) + (voff)[_i]), (PG8_LAS unsigned*)(lds + (bufoff) + ldsw + _i * 8192), 16, 0, 0); } while (0)
; #define PG8_LDA(dst, b, h) do { _Pragma("unroll") for (int m = 0; m < 4; ++m) _Pragma("unroll") for (int k = 0; k < 2; ++k) dst[m][k] = *(const PG8_LAS bf16x8*)(lds + PG8_SA(b, h) + aoff + m * 2048 + k * 1024); } while (0)
; #define PG8_LDB(dst, b, h) do { _Pragma("unroll") for (int n = 0; n < 2; ++n) _Pragma("unroll") for (int k = 0; k < 2; ++k) dst[n][k] = *(const PG8_LAS bf16x8*)(lds + PG8_SB(b, h) + boff + n * 2048 + k * 1024); } while (0)
; #define PG8_MMA(ai, bj, At, Bt) do { __builtin_amdgcn_s_setprio(1); _Pragma("unroll") for (int m = 0; m < 4; ++m) _Pragma("unroll") for (int n = 0; n < 2; ++n) _Pragma("unroll") for (int k = 0; k < 2; ++k) \
;         acc[ai][bj][m][n] = __builtin_amdgcn_mfma_f32_16x16x32_bf16(Bt[n][k], At[m][k], acc[ai][bj][m][n], 0, 0, 0); __builtin_amdgcn_s_setprio(0); } while (0)
; #define PG8_WAIT_V(n) asm volatile("s_waitcnt vmcnt(" #n ")" ::: "memory")
; #define PG8_WAIT_L(n) asm volatile("s_waitcnt lgkmcnt(" #n ")" ::: "memory")
; #define PG8_BAR __builtin_amdgcn_s_barrier()
; #define PG8_SCHED __builtin_amdgcn_sched_barrier(0)
; template <class Epi, class Sched, bool ALIGN_EPI = false, bool SP2 = false>
; __device__ __forceinline__ void gemm_phase(PG8_LAS unsigned char* lds, const Gemm g, const Sched& S, const Epi& E) {
;     ...
;             PG8_LDA(At, 0, 1); PG8_STAGE(PG8_SB(0, 0), b2, voffB); PG8_STAGE(PG8_SB(0, 1), b2 + hstep, voffB); PG8_STAGE(PG8_SA(0, 0), a2, voffA);
;             PG8_WAIT_V(8); PG8_WAIT_L(0); PG8_BAR; PG8_MMA(1, 0, At, B0); PG8_MMA(1, 1, At, B1); PG8_BAR; PG8_SCHED;
;             PG8_LDB(B0, 1, 0); PG8_LDB(B1, 1, 1); PG8_SCHED; PG8_LDA(At, 1, 0); PG8_STAGE(PG8_SA(0, 1), a2 + hstep, voffA);
;             PG8_WAIT_V(8); PG8_WAIT_L(0); PG8_BAR; PG8_MMA(0, 0, At, B0); PG8_MMA(0, 1, At, B1); PG8_BAR; PG8_SCHED;
.Ltm_t1:
	s_setprio 1
	v_mfma_f32_16x16x32_bf16 v[62:65], v[114:117], v[180:183], v[62:65]
	s_add_u32 s50, s42, 0x80000
	v_mfma_f32_16x16x32_bf16 v[58:61], v[130:133], v[180:183], v[58:61]
	s_addc_u32 s51, s43, 0
	v_mfma_f32_16x16x32_bf16 v[46:49], v[114:117], v[188:191], v[46:49]
	s_mov_b32 m0, s10
	v_mfma_f32_16x16x32_bf16 v[42:45], v[130:133], v[188:191], v[42:45]
	global_load_lds_dwordx4 v158, s[50:51]
	v_mfma_f32_16x16x32_bf16 v[30:33], v[114:117], v[196:199], v[30:33]
	s_mov_b32 m0, s11
	v_mfma_f32_16x16x32_bf16 v[26:29], v[130:133], v[196:199], v[26:29]
	global_load_lds_dwordx4 v156, s[50:51]
	v_mfma_f32_16x16x32_bf16 v[14:17], v[114:117], v[208:211], v[14:17]
	v_mfma_f32_16x16x32_bf16 v[10:13], v[130:133], v[208:211], v[10:13]
	v_mfma_f32_16x16x32_bf16 v[62:65], v[118:121], v[184:187], v[62:65]
	v_mfma_f32_16x16x32_bf16 v[58:61], v[134:137], v[184:187], v[58:61]
	v_mfma_f32_16x16x32_bf16 v[46:49], v[118:121], v[192:195], v[46:49]
	v_mfma_f32_16x16x32_bf16 v[42:45], v[134:137], v[192:195], v[42:45]
	v_mfma_f32_16x16x32_bf16 v[30:33], v[118:121], v[200:203], v[30:33]
	v_mfma_f32_16x16x32_bf16 v[26:29], v[134:137], v[200:203], v[26:29]
	v_mfma_f32_16x16x32_bf16 v[14:17], v[118:121], v[230:233], v[14:17]
	v_mfma_f32_16x16x32_bf16 v[10:13], v[134:137], v[230:233], v[10:13]
	s_setprio 0
.Ltm_e1:
	s_barrier
	ds_read_b128 v[114:117], v244
	ds_read_b128 v[118:121], v244 offset:1024
	ds_read_b128 v[130:133], v244 offset:2048
	ds_read_b128 v[134:137], v244 offset:3072
	ds_read_b128 v[180:183], v178 offset:32768
	ds_read_b128 v[184:187], v178 offset:33792
	ds_read_b128 v[188:191], v178 offset:34816
	ds_read_b128 v[192:195], v178 offset:35840
	ds_read_b128 v[196:199], v178 offset:36864
	ds_read_b128 v[200:203], v178 offset:37888
	ds_read_b128 v[208:211], v178 offset:38912
	ds_read_b128 v[230:233], v178 offset:39936
	s_mov_b64 vcc, s[2:3]
	s_cbranch_vccnz .Ltm_s2
	s_waitcnt vmcnt(6)
.Ltm_s2:
	s_waitcnt lgkmcnt(0)
	s_barrier
	s_mov_b64 vcc, s[2:3]
	s_cbranch_vccz .Ltm_t2
	s_setprio 1
	v_mfma_f32_16x16x32_bf16 v[142:145], v[114:117], v[180:183], v[142:145]
	s_add_u32 s50, s42, 0x80000
	v_mfma_f32_16x16x32_bf16 v[138:141], v[130:133], v[180:183], v[138:141]
	s_addc_u32 s51, s43, 0
	v_mfma_f32_16x16x32_bf16 v[110:113], v[114:117], v[188:191], v[110:113]
	s_mov_b32 m0, s10
	v_mfma_f32_16x16x32_bf16 v[106:109], v[130:133], v[188:191], v[106:109]
	global_load_lds_dwordx4 v158, s[50:51]
	v_mfma_f32_16x16x32_bf16 v[94:97], v[114:117], v[196:199], v[94:97]
	s_mov_b32 m0, s11
	v_mfma_f32_16x16x32_bf16 v[90:93], v[130:133], v[196:199], v[90:93]
	global_load_lds_dwordx4 v156, s[50:51]
	v_mfma_f32_16x16x32_bf16 v[78:81], v[114:117], v[208:211], v[78:81]
	v_mfma_f32_16x16x32_bf16 v[74:77], v[130:133], v[208:211], v[74:77]
	v_mfma_f32_16x16x32_bf16 v[142:145], v[118:121], v[184:187], v[142:145]
	v_mfma_f32_16x16x32_bf16 v[138:141], v[134:137], v[184:187], v[138:141]
	v_mfma_f32_16x16x32_bf16 v[110:113], v[118:121], v[192:195], v[110:113]
	v_mfma_f32_16x16x32_bf16 v[106:109], v[134:137], v[192:195], v[106:109]
	v_mfma_f32_16x16x32_bf16 v[94:97], v[118:121], v[200:203], v[94:97]
	v_mfma_f32_16x16x32_bf16 v[90:93], v[134:137], v[200:203], v[90:93]
	v_mfma_f32_16x16x32_bf16 v[78:81], v[118:121], v[230:233], v[78:81]
	v_mfma_f32_16x16x32_bf16 v[74:77], v[134:137], v[230:233], v[74:77]
	s_setprio 0
	s_waitcnt vmcnt(6)
	s_branch .Ltm_e2
.Ltm_t2:
	s_setprio 1
	v_mfma_f32_16x16x32_bf16 v[142:145], v[114:117], v[180:183], v[142:145]
	s_add_i32 vcc_lo, s90, s6
	v_mfma_f32_16x16x32_bf16 v[138:141], v[130:133], v[180:183], v[138:141]
	s_add_u32 s50, s40, 0x80
	v_mfma_f32_16x16x32_bf16 v[110:113], v[114:117], v[188:191], v[110:113]
	s_addc_u32 s51, s41, 0
	v_mfma_f32_16x16x32_bf16 v[106:109], v[130:133], v[188:191], v[106:109]
	s_mov_b32 m0, vcc_lo
	v_mfma_f32_16x16x32_bf16 v[94:97], v[114:117], v[196:199], v[94:97]
	global_load_lds_dwordx4 v0, s[50:51]
	v_mfma_f32_16x16x32_bf16 v[90:93], v[130:133], v[196:199], v[90:93]
	s_add_i32 m0, vcc_lo, 0x2000
	v_mfma_f32_16x16x32_bf16 v[78:81], v[114:117], v[208:211], v[78:81]
	global_load_lds_dwordx4 v154, s[50:51]
	v_mfma_f32_16x16x32_bf16 v[74:77], v[130:133], v[208:211], v[74:77]
	s_add_u32 s50, s42, 0x80
	v_mfma_f32_16x16x32_bf16 v[142:145], v[118:121], v[184:187], v[142:145]
	s_addc_u32 s51, s43, 0
	v_mfma_f32_16x16x32_bf16 v[138:141], v[134:137], v[184:187], v[138:141]
	s_mov_b32 m0, s13
	v_mfma_f32_16x16x32_bf16 v[110:113], v[118:121], v[192:195], v[110:113]
	global_load_lds_dwordx4 v158, s[50:51]
	v_mfma_f32_16x16x32_bf16 v[106:109], v[134:137], v[192:195], v[106:109]
	s_mov_b32 m0, s25
	v_mfma_f32_16x16x32_bf16 v[94:97], v[118:121], v[200:203], v[94:97]
	global_load_lds_dwordx4 v156, s[50:51]
	v_mfma_f32_16x16x32_bf16 v[90:93], v[134:137], v[200:203], v[90:93]
	v_mfma_f32_16x16x32_bf16 v[78:81], v[118:121], v[230:233], v[78:81]
	v_mfma_f32_16x16x32_bf16 v[74:77], v[134:137], v[230:233], v[74:77]
	s_setprio 0
; #define PG8_STAGE(bufoff, gbase, voff) do { _Pragma("unroll") for (int _i = 0; _i < 2; ++_i) \
;         __builtin_amdgcn_global_load_lds((const unsigned*)((const char*)(gbase) + (voff)[_i]), (PG8_LAS unsigned*)(lds + (bufoff) + ldsw + _i * 8192), 16, 0, 0); } while (0)
; #define PG8_LDA(dst, b, h) do { _Pragma("unroll") for (int m = 0; m < 4; ++m) _Pragma("unroll") for (int k = 0; k < 2; ++k) dst[m][k] = *(const PG8_LAS bf16x8*)(lds + PG8_SA(b, h) + aoff + m * 2048 + k * 1024); } while (0)
; #define PG8_MMA(ai, bj, At, Bt) do { __builtin_amdgcn_s_setprio(1); _Pragma("unroll") for (int m = 0; m < 4; ++m) _Pragma("unroll") for (int n = 0; n < 2; ++n) _Pragma("unroll") for (int k = 0; k < 2; ++k) \
;         acc[ai][bj][m][n] = __builtin_amdgcn_mfma_f32_16x16x32_bf16(Bt[n][k], At[m][k], acc[ai][bj][m][n], 0, 0, 0); __builtin_amdgcn_s_setprio(0); } while (0)
; #define PG8_WAIT_V(n) asm volatile("s_waitcnt vmcnt(" #n ")" ::: "memory")
; #define PG8_WAIT_L(n) asm volatile("s_waitcnt lgkmcnt(" #n ")" ::: "memory")
; #define PG8_BAR __builtin_amdgcn_s_barrier()
; #define PG8_SCHED __builtin_amdgcn_sched_barrier(0)
; template <class Epi, class Sched, bool ALIGN_EPI = false, bool SP2 = false>
; __device__ __forceinline__ void gemm_phase(PG8_LAS unsigned char* lds, const Gemm g, const Sched& S, const Epi& E) {
;     ...
;         for (int t = 0; t < nt; t += 2) {
;     ...
;             PG8_LDA(At, 1, 1); PG8_STAGE(PG8_SB(1, 0), b3, voffB); PG8_STAGE(PG8_SB(1, 1), b3 + hstep, voffB); PG8_STAGE(PG8_SA(1, 0), a3, voffA);
;             PG8_WAIT_V(8); PG8_WAIT_L(0); PG8_BAR; PG8_MMA(1, 0, At, B0); PG8_MMA(1, 1, At, B1); PG8_BAR; PG8_SCHED;
.Ltm_e2:
	s_barrier
	ds_read_b128 v[180:183], v178 offset:49152
	ds_read_b128 v[184:187], v178 offset:50176
	ds_read_b128 v[188:191], v178 offset:51200
	ds_read_b128 v[192:195], v178 offset:52224
	ds_read_b128 v[196:199], v178 offset:53248
	ds_read_b128 v[200:203], v178 offset:54272
	ds_read_b128 v[208:211], v178 offset:55296
	ds_read_b128 v[230:233], v178 offset:56320
	s_mov_b64 vcc, s[2:3]
	s_cbranch_vccnz .Ltm_s3
	s_waitcnt vmcnt(6)
.Ltm_s3:
	s_waitcnt lgkmcnt(0)
	s_barrier
	s_mov_b64 vcc, s[2:3]
	s_cbranch_vccz .Ltm_t3
	s_setprio 1
	v_mfma_f32_16x16x32_bf16 v[62:65], v[114:117], v[180:183], v[62:65]
	s_add_i32 vcc_lo, s90, s6
	v_mfma_f32_16x16x32_bf16 v[58:61], v[130:133], v[180:183], v[58:61]
	s_add_u32 s50, s40, 0x80
	v_mfma_f32_16x16x32_bf16 v[46:49], v[114:117], v[188:191], v[46:49]
	s_addc_u32 s51, s41, 0
	v_mfma_f32_16x16x32_bf16 v[42:45], v[130:133], v[188:191], v[42:45]
	s_mov_b32 m0, vcc_lo
	v_mfma_f32_16x16x32_bf16 v[30:33], v[114:117], v[196:199], v[30:33]
	global_load_lds_dwordx4 v0, s[50:51]
	v_mfma_f32_16x16x32_bf16 v[26:29], v[130:133], v[196:199], v[26:29]
	s_add_i32 m0, vcc_lo, 0x2000
	v_mfma_f32_16x16x32_bf16 v[14:17], v[114:117], v[208:211], v[14:17]
	global_load_lds_dwordx4 v154, s[50:51]
	v_mfma_f32_16x16x32_bf16 v[10:13], v[130:133], v[208:211], v[10:13]
	s_add_u32 s50, s42, 0x80
	v_mfma_f32_16x16x32_bf16 v[62:65], v[118:121], v[184:187], v[62:65]
	s_addc_u32 s51, s43, 0
	v_mfma_f32_16x16x32_bf16 v[58:61], v[134:137], v[184:187], v[58:61]
	s_mov_b32 m0, s13
	v_mfma_f32_16x16x32_bf16 v[46:49], v[118:121], v[192:195], v[46:49]
	global_load_lds_dwordx4 v158, s[50:51]
	v_mfma_f32_16x16x32_bf16 v[42:45], v[134:137], v[192:195], v[42:45]
	s_mov_b32 m0, s25
	v_mfma_f32_16x16x32_bf16 v[30:33], v[118:121], v[200:203], v[30:33]
	global_load_lds_dwordx4 v156, s[50:51]
	v_mfma_f32_16x16x32_bf16 v[26:29], v[134:137], v[200:203], v[26:29]
	v_mfma_f32_16x16x32_bf16 v[14:17], v[118:121], v[230:233], v[14:17]
	v_mfma_f32_16x16x32_bf16 v[10:13], v[134:137], v[230:233], v[10:13]
	s_setprio 0
	s_waitcnt vmcnt(6)
	s_branch .Ltm_e3
.Ltm_t3:
	s_setprio 1
	v_mfma_f32_16x16x32_bf16 v[62:65], v[114:117], v[180:183], v[62:65]
	v_mfma_f32_16x16x32_bf16 v[58:61], v[130:133], v[180:183], v[58:61]
	v_mfma_f32_16x16x32_bf16 v[46:49], v[114:117], v[188:191], v[46:49]
	v_mfma_f32_16x16x32_bf16 v[42:45], v[130:133], v[188:191], v[42:45]
	v_mfma_f32_16x16x32_bf16 v[30:33], v[114:117], v[196:199], v[30:33]
	v_mfma_f32_16x16x32_bf16 v[26:29], v[130:133], v[196:199], v[26:29]
	v_mfma_f32_16x16x32_bf16 v[14:17], v[114:117], v[208:211], v[14:17]
	v_mfma_f32_16x16x32_bf16 v[10:13], v[130:133], v[208:211], v[10:13]
	v_mfma_f32_16x16x32_bf16 v[62:65], v[118:121], v[184:187], v[62:65]
	v_mfma_f32_16x16x32_bf16 v[58:61], v[134:137], v[184:187], v[58:61]
	v_mfma_f32_16x16x32_bf16 v[46:49], v[118:121], v[192:195], v[46:49]
	v_mfma_f32_16x16x32_bf16 v[42:45], v[134:137], v[192:195], v[42:45]
	v_mfma_f32_16x16x32_bf16 v[30:33], v[118:121], v[200:203], v[30:33]
	v_mfma_f32_16x16x32_bf16 v[26:29], v[134:137], v[200:203], v[26:29]
	v_mfma_f32_16x16x32_bf16 v[14:17], v[118:121], v[230:233], v[14:17]
	v_mfma_f32_16x16x32_bf16 v[10:13], v[134:137], v[230:233], v[10:13]
	s_setprio 0
.Ltm_e3:
	s_add_i32 s46, s46, 2
	s_add_u32 s34, s34, 0x100
	s_addc_u32 s35, s35, 0
	s_add_u32 s44, s44, 0x100
	s_addc_u32 s45, s45, 0
	s_cmp_gt_u32 s46, 29
	s_barrier
	s_cbranch_scc0 .Ltail_loop
	s_branch .Ltail_join
